# P6 order swap for XCD slots {0,2,3,5,6} (5 of 8 swapped)
# baseline (speedup 1.0000x reference)
; __global__ void __launch_bounds__(512, 2) fwd_mega(Params P) {
;     ...
;     { EpiUp E{(bf16_t*)(ws + OFF_FFB)}; run_gemm(glds, (const bf16_t*)(ws + OFF_H1B), (const bf16_t*)(ws + OFF_WUP), 4096, DM, E, wid_s); }
;     { EpiGate E{(bf16_t*)(ws + OFF_PG), P.in[18]}; run_gemm(glds, (const bf16_t*)(ws + OFF_H1B), (const bf16_t*)(ws + OFF_WG), DM, DM, E, wid_s); }
.Lp6_up_entry:
	s_add_u32 s4, s80, 0x4800000
	v_readlane_b32 s0, v255, 31
	s_addc_u32 s5, s81, 0
	s_lshl_b32 s0, s0, 5
	s_and_b32 s36, s0, 0x60
	s_lshl_b32 s37, s36, 7
	s_cmpk_gt_i32 s33, 0x3ff
	s_waitcnt lgkmcnt(0)
	s_barrier
	v_mbcnt_lo_u32_b32 v8, -1, 0
	v_mbcnt_hi_u32_b32 v8, -1, v8
	s_cbranch_scc1 .LBB0_830
	s_cmp_eq_u32 s98, 0
	s_cbranch_scc0 .Lp6_up_go
	s_and_b32 s99, s33, 7
	s_mov_b32 s100, 0x6d
	s_bitcmp1_b32 s100, s99
	s_cbranch_scc0 .Lp6_up_go
	s_mov_b32 s98, 1
	s_branch .LBB0_830
